# next-layer weight transposes moved from the FF1 tail (128 WGs idle one K=1024 tile) to the FF2 tail join point, where WGs 32..255 idle for a K=4096 tile; same workers bx>=128, same code
# baseline (speedup 1.0000x reference)
; #define LAS __attribute__((address_space(3)))
; __global__ void __launch_bounds__(NTHR, 2) trunk_fwd(Args a) {
;     ...
;         LAS float* scr = (LAS float*)(lds + wave * 16384);
;         constexpr int I_IN = 16 * 72, I_OUT = 16 * 32, I_1 = 16 * 128, I_2 = 64 * 32, I_L = I_IN + I_OUT + I_1 + I_2;
;         for (int it = gw; it < DEPTH * I_L; it += ngw) { const int l = it / I_L; int r = it % I_L;
;             if (r < I_IN) { transpose_item<true>(a.w_in + (size_t)l * DM * DIN, DM, DIN, WT_IN + (size_t)l * DIN * DM, scr, r, lane); continue; } r -= I_IN;
;             if (r < I_OUT) { transpose_item<true>(a.w_out + (size_t)l * DM * DM, DM, DM, WT_OUT + (size_t)l * DM * DM, scr, r, lane); continue; } r -= I_OUT;
;             if (r < I_1) { transpose_item<true>(a.w_ff1 + (size_t)l * DM * DFF, DM, DFF, WT_1 + (size_t)l * DFF * DM, scr, r, lane); continue; } r -= I_1;
;             transpose_item<true>(a.w_ff2 + (size_t)l * DFF * DM, DFF, DM, WT_2 + (size_t)l * DM * DFF, scr, r, lane); }
.LBB0_1718:
	v_readlane_b32 s37, v253, 41
	v_readlane_b32 s30, v253, 57
	v_readlane_b32 s31, v253, 58
	v_readfirstlane_b32 s38, v212
	s_nop 3
	s_cmp_lt_u32 s79, 0x80
	s_cbranch_scc1 .Ldtx_skip
	s_cmp_gt_u32 s37, 2
	s_cbranch_scc1 .Ldtx_skip
	s_load_dwordx2 s[28:29], s[30:31], 0x30
	s_load_dwordx2 s[18:19], s[30:31], 0x88
	s_load_dwordx4 s[24:27], s[30:31], 0xa0
	s_mov_b32 s20, s4
	s_mov_b32 s21, s5
	s_mov_b32 s22, s6
	s_mov_b32 s23, s12
	s_mov_b32 s34, s14
	s_mov_b32 s35, s15
	s_mov_b32 s36, s46
	s_add_u32 s37, s37, 1
	s_mul_i32 s12, s37, 0x1680
	s_add_u32 s39, s12, 0x1680
	s_lshr_b32 s38, s38, 6
	s_sub_u32 s4, s79, 0x80
	s_lshl_b32 s4, s4, 3
	s_add_u32 s12, s12, s4
	s_add_u32 s12, s12, s38
	s_movk_i32 s38, 0x400
	s_waitcnt lgkmcnt(0)

; __device__ __forceinline__ void xcd_barrier(const XcdBarrier& b) {
;     asm volatile("s_waitcnt vmcnt(0)" ::: "memory");
;     __syncthreads();
;     if (threadIdx.x == 0) {
;         unsigned* bar = b.bar;
;         __builtin_amdgcn_s_waitcnt(0);
;         unsigned nloc = b.st[0], nx = b.st[1];
;         if (nloc == 0u) { xcd_barrier_complete(bar, b.x, nloc, nx); b.st[0] = nloc; b.st[1] = nx; }
.Ldtx_done:
	s_waitcnt vmcnt(0) lgkmcnt(0)
	s_mov_b32 s4, s20
	s_mov_b32 s5, s21
	s_mov_b32 s6, s22
	s_mov_b32 s12, s23
	s_mov_b32 s14, s34
	s_mov_b32 s15, s35
	s_mov_b32 s46, s36
.Ldtx_skip:
	s_getreg_b32 s8, hwreg(HW_REG_XCC_ID, 0, 4)
	s_waitcnt vmcnt(0)
	v_readlane_b32 s2, v252, 0
	v_readlane_b32 s3, v252, 1
	s_waitcnt vmcnt(0)
	s_barrier
	s_and_saveexec_b64 s[0:1], s[2:3]
	s_cbranch_execz .LBB0_1770
	v_readlane_b32 s2, v255, 46
	s_waitcnt vmcnt(0) expcnt(0) lgkmcnt(0)
	s_and_b32 s16, s8, 15
	v_mov_b32_e32 v0, s2
	ds_read_b32 v3, v0
	v_readlane_b32 s2, v255, 47
	s_waitcnt lgkmcnt(0)
	v_cmp_ne_u32_e32 vcc, 0, v3
	v_mov_b32_e32 v0, s2
	ds_read_b32 v2, v0
	s_cbranch_vccnz .LBB0_1734
	s_mov_b32 s17, 1
	s_branch .LBB0_1722
